# v23 + grid-barrier release (per-XCD generation atomic) issued as global atomic without waiting for its ack
# speedup vs baseline: 1.0028x; 1.0028x over previous
; __device__ __forceinline__ unsigned xb_add(unsigned* p, unsigned v) { return __hip_atomic_fetch_add(p, v, __ATOMIC_RELAXED, __HIP_MEMORY_SCOPE_AGENT); }
; __device__ __forceinline__ void xcd_barrier(const int wv, const XcdBarrier& b) {
;     ...
;             __builtin_amdgcn_fence(__ATOMIC_ACQUIRE, "agent");
;             xb_add(&bar[XB_XGEN(b.x)], 1u);
;             asm volatile("s_waitcnt vmcnt(0)" ::: "memory");
.LBB0_127:
	s_or_b64 exec, exec, s[4:5]
	v_mov_b32_e32 v0, s25
	v_add_co_u32_e32 v0, vcc, 0x2000, v0
	v_mov_b32_e32 v1, s24
	s_nop 0
	v_addc_co_u32_e32 v1, vcc, 0, v1, vcc
	v_mov_b32_e32 v2, 1
	s_waitcnt vmcnt(0) lgkmcnt(0)
	buffer_inv sc1
	global_atomic_add v[0:1], v2, off offset:1024

; __device__ __forceinline__ unsigned xb_add(unsigned* p, unsigned v) { return __hip_atomic_fetch_add(p, v, __ATOMIC_RELAXED, __HIP_MEMORY_SCOPE_AGENT); }
; __device__ __forceinline__ void xcd_barrier(const int wv, const XcdBarrier& b) {
;     ...
;             __builtin_amdgcn_fence(__ATOMIC_ACQUIRE, "agent");
;             xb_add(&bar[XB_XGEN(b.x)], 1u);
;             asm volatile("s_waitcnt vmcnt(0)" ::: "memory");
.LBB0_130:
	s_or_b64 exec, exec, s[2:3]
	v_add_co_u32_e32 v2, vcc, 0x2000, v2
	s_waitcnt vmcnt(0) lgkmcnt(0)
	buffer_inv sc1
	v_addc_co_u32_e32 v3, vcc, 0, v3, vcc
	global_atomic_add v[2:3], v184, off offset:1024

; __device__ __forceinline__ unsigned xb_add(unsigned* p, unsigned v) { return __hip_atomic_fetch_add(p, v, __ATOMIC_RELAXED, __HIP_MEMORY_SCOPE_AGENT); }
; __device__ __forceinline__ void xcd_barrier(const int wv, const XcdBarrier& b) {
;     ...
;             __builtin_amdgcn_fence(__ATOMIC_ACQUIRE, "agent");
;             xb_add(&bar[XB_XGEN(b.x)], 1u);
;             asm volatile("s_waitcnt vmcnt(0)" ::: "memory");
.LBB0_645:
	s_or_b64 exec, exec, s[2:3]
	v_add_co_u32_e32 v0, vcc, 0x2000, v0
	v_mov_b32_e32 v2, 1
	s_nop 0
	v_addc_co_u32_e32 v1, vcc, 0, v1, vcc
	s_waitcnt vmcnt(0) lgkmcnt(0)
	buffer_inv sc1
	global_atomic_add v[0:1], v2, off offset:1024
